# strategy 7.4: one static s_setprio 1 for waves 4..7 (second half) at kernel entry
# baseline (speedup 1.0000x reference)
; #define PG8_LAS __attribute__((address_space(3)))
; #define LAS __attribute__((address_space(3)))
; __global__ void __launch_bounds__(NTHREADS, 2) mk_fwd(Args args) {
;     extern __shared__ __attribute__((aligned(16))) unsigned char lds_raw[];
;     LAS unsigned char* lds = (LAS unsigned char*)lds_raw;
;     const int tid = threadIdx.x, lane = tid & 63, wave = __builtin_amdgcn_readfirstlane(tid >> 6);
;     const int G = gridDim.x, blk = blockIdx.x;
;     unsigned char* ws = args.ws;
;     const int lo = args.ph_lo, hi = args.ph_hi;
;     ...
;     for (int u = tid; u < 64; u += NTHREADS) ((LAS unsigned*)(lds + LDS_CTL_OFF))[u] = 0u;
;     __syncthreads();
;     const XcdBarrier bar = xcd_barrier_post((unsigned*)(ws + WS_BAR), (volatile LAS unsigned*)(lds + LDS_CTL_OFF + 32));
;     float* SSQ = (float*)(ws + WS_PART); PG8_LAS float* RED = (PG8_LAS float*)(lds + LDS_CTL_OFF + 1024); LAS float* RS = (LAS float*)(lds + LDS_CTL_OFF + 5120); const float* COS = (const float*)(ws + WS_COS); const float* SIN = (const float*)(ws + WS_SIN);
;     bf16_t* XB = (bf16_t*)(ws + WS_XB); bf16_t* PROJ = (bf16_t*)(ws + WS_PROJ); bf16_t* ATT = (bf16_t*)(ws + WS_ATT); bf16_t* SGU = (bf16_t*)(ws + WS_SGU);
;     bf16_t* MRG = (bf16_t*)(ws + WS_MRG); bf16_t* TMP = (bf16_t*)(ws + WS_TMP); bf16_t* ACT = (bf16_t*)(ws + WS_ACT);
;     if (KON(0) && IN(0)) { const int vcu = (G % 8 == 0) ? (blk % 8) * (G / 8) + blk / 8 : blk; p0_prologue(args, vcu * NWAVES + wave, G * NWAVES, lane, 0x000Fu | 0x0010u | 0x0800u, true, 0x0810u, 0, 10); }
.LBB0_5:
	s_or_b64 exec, exec, s[4:5]
	s_lshr_b32 s2, s2, 6
	s_cmp_ge_u32 s2, 4
	s_cbranch_scc0 .Lprio_done
	s_setprio 1
.Lprio_done:
	s_add_u32 s4, s92, 0x40000
	s_addc_u32 s5, s93, 0
	v_writelane_b32 v250, s4, 36
	s_nop 1
	v_writelane_b32 v250, s5, 37
	s_add_u32 s4, s92, 0x80000
	s_addc_u32 s5, s93, 0
	v_writelane_b32 v250, s4, 38
	s_cmp_lt_i32 s94, 1
	s_nop 0
	v_writelane_b32 v250, s5, 39
	s_cselect_b64 s[4:5], -1, 0
	s_cmp_gt_i32 s95, 0
	s_cselect_b64 s[6:7], -1, 0
	s_and_b64 s[10:11], s[4:5], s[6:7]
	s_andn2_b64 vcc, exec, s[10:11]
	s_cbranch_vccnz .LBB0_78
	s_and_b32 s4, s3, 7
	s_mov_b32 s13, 0
	s_cmp_lg_u32 s4, 0
	s_mov_b32 s4, s85
	s_cbranch_scc1 .LBB0_8
	s_ashr_i32 s5, s85, 31
	s_lshr_b32 s5, s5, 29
	s_add_i32 s5, s85, s5
	s_and_b32 s6, s5, -8
	s_ashr_i32 s4, s3, 3
	s_sub_i32 s6, s85, s6
	s_mul_i32 s4, s4, s6
	s_ashr_i32 s5, s5, 3
	s_add_i32 s4, s4, s5
